# phase A weight transposition loop: loop-head waits no longer drain the previous tile's two stores
# baseline (speedup 1.0000x reference)
; #define TIDX tid_()
; #define BIDX bid_()
; #define GDIM gdim_()
; __device__ __forceinline__ void tr_to_lds(const float (&v)[16], float* sf, int tid) {
;     const int nl = tid & 63, kb = tid >> 6;
; #pragma unroll
;     for (int i = 0; i < 16; ++i) sf[(i * 8 + kb) * 65 + nl] = v[i];
; }
; __device__ __forceinline__ void tr_store(const TrTile& t, const float* sf, int tid) {
;     const int nl2 = tid >> 3;
; #pragma unroll
;     for (int hk = 0; hk < 2; ++hk) { const int kc = (tid & 7) * 8 + hk * 64;
; __device__ void weight_tiles(const Params& p, float* sf, int l) {
;     constexpr int T_L = (NPAD / 64) * 16 + 32 * 32;
;     const int tid = TIDX, gd = GDIM;
;     const int t_end = (l + 1) * T_L;
;     int t = l * T_L + BIDX;
;     float v[16];
;     __syncthreads();
;     if (t < t_end) { const TrTile c0 = tr_tile(p, t); tr_load(c0, v, tid); }
;     while (t < t_end) {
.LBB0_488:
	s_andn2_b64 vcc, exec, s[6:7]
	s_cbranch_vccnz .LBB0_533
	v_lshlrev_b32_e32 v0, 3, v2
	v_and_b32_e32 v0, 56, v0
	v_ashrrev_i32_e32 v10, 3, v2
	v_mul_u32_u24_e32 v11, 0x41, v0
	s_add_u32 s6, s4, 0x3500000
	v_and_b32_e32 v8, 63, v2
	v_ashrrev_i32_e32 v9, 6, v2
	s_movk_i32 s12, 0x104
	v_lshlrev_b32_e32 v2, 2, v10
	v_lshlrev_b32_e32 v12, 2, v11
	s_addc_u32 s7, s5, 0
	v_lshl_add_u32 v1, v8, 2, 0
	v_mul_lo_u32 v3, v9, s12
	v_add3_u32 v11, 0, v2, v12
	v_add3_u32 v12, 0, v12, v2
	s_lshl_b32 s12, s24, 1
	v_add_u32_e32 v13, 0x4100, v12
	s_lshl_b32 s25, s24, 7
	s_lshl_b32 s26, s3, 7
	s_lshl_b32 s27, s24, 2
	s_lshl_b32 s28, s3, 2
	s_add_i32 s29, s12, 0x7fffe580
	s_lshl_b32 s30, s3, 1
	v_add_u32_e32 v14, v1, v3
	v_lshlrev_b32_e32 v0, 1, v0
	s_waitcnt vmcnt(0)
	s_branch .LBB0_492

; #define TIDX tid_()
; #define BIDX bid_()
; #define GDIM gdim_()
; __device__ __forceinline__ void tr_to_lds(const float (&v)[16], float* sf, int tid) {
;     const int nl = tid & 63, kb = tid >> 6;
; #pragma unroll
;     for (int i = 0; i < 16; ++i) sf[(i * 8 + kb) * 65 + nl] = v[i];
; }
; __device__ __forceinline__ TrTile tr_tile(const Params& p, int t) {
;     constexpr int T_IN = (NPAD / 64) * 16, T_OUT = 32 * 32;
;     const int l = t / (T_IN + T_OUT), r = t % (T_IN + T_OUT);
;     TrTile o;
;     if (r < T_IN) { o.src = p.w_in + (size_t)l * 2048 * NIN; o.dst = p.wt_in + (size_t)l * (SZ_WL / 2); o.Nsrc = NIN; o.K = 2048; o.n0 = (r >> 4) * 64; o.k0 = (r & 15) * 128; o.perm = 1; }
;     else { const int r2 = r - T_IN; o.src = p.w_out + (size_t)l * 4096 * 2048; o.dst = p.wt_out + (size_t)l * (SZ_WL / 2); o.Nsrc = 2048; o.K = 4096; o.n0 = (r2 >> 5) * 64; o.k0 = (r2 & 31) * 128; o.perm = 0; }
;     return o;
; }
; __device__ void weight_tiles(const Params& p, float* sf, int l) {
;     constexpr int T_L = (NPAD / 64) * 16 + 32 * 32;
;     const int tid = TIDX, gd = GDIM;
;     const int t_end = (l + 1) * T_L;
;     int t = l * T_L + BIDX;
;     float v[16];
;     __syncthreads();
;     if (t < t_end) { const TrTile c0 = tr_tile(p, t); tr_load(c0, v, tid); }
;     while (t < t_end) {
;         tr_to_lds(v, sf, tid);
;         __syncthreads();
;         const int tn = t + gd;
;         if (tn < t_end) { const TrTile nxt = tr_tile(p, tn); tr_load(nxt, v, tid); }
.LBB0_492:
	s_add_i32 s31, s24, s3
	s_cmpk_gt_i32 s31, 0x113f
	s_cselect_b64 s[12:13], -1, 0
	s_and_b64 vcc, exec, s[12:13]
	s_waitcnt vmcnt(3)
	ds_write_b32 v14, v5
	s_waitcnt vmcnt(2)
	ds_write_b32 v14, v6 offset:2080
	ds_write_b32 v14, v4 offset:4160
	ds_write_b32 v14, v7 offset:6240
	ds_write_b32 v14, v16 offset:8320
	ds_write_b32 v14, v17 offset:10400
	ds_write_b32 v14, v15 offset:12480
	ds_write_b32 v14, v18 offset:14560
	ds_write_b32 v14, v20 offset:16640
	ds_write_b32 v14, v21 offset:18720
	ds_write_b32 v14, v19 offset:20800
	ds_write_b32 v14, v22 offset:22880
	ds_write_b32 v14, v24 offset:24960
	ds_write_b32 v14, v25 offset:27040
	ds_write_b32 v14, v26 offset:29120
	ds_write_b32 v14, v23 offset:31200
	s_waitcnt lgkmcnt(0)
	s_barrier
	s_cbranch_vccnz .LBB0_529
	s_mul_hi_i32 s14, s31, 0x76b981db
	s_lshr_b32 s15, s14, 31
	s_ashr_i32 s14, s14, 11
	s_add_i32 s16, s14, s15
	s_mul_i32 s14, s16, 0xffffeec0
	s_add_i32 s14, s31, s14
	s_cmpk_gt_i32 s14, 0xd3f
	s_cselect_b64 s[20:21], -1, 0
	s_ashr_i32 s17, s16, 31
	s_mov_b64 s[14:15], -1
	s_and_b64 vcc, exec, s[20:21]
	s_cbranch_vccnz .LBB0_495
	s_mul_i32 s15, s16, 0x68c0000
	s_mul_hi_i32 s14, s16, 0x68c0000
	s_add_u32 s18, s8, s15
	s_addc_u32 s19, s9, s14
	s_mul_i32 s14, s16, 0xffffbb00
	s_add_i32 s15, s28, s27
	s_add_i32 s14, s15, s14
	s_and_b32 s34, s14, 0xffffffc0
	s_mov_b64 s[14:15], 0
